# FFN hidden (SwiGLU epilogue) stores marked nt so the residual stream can stay cache-resident
# baseline (speedup 1.0000x reference)
.LBB0_687:
	v_mul_f32_e32 v147, 0xbfb8aa3b, v126
	v_exp_f32_e32 v147, v147
	v_readlane_b32 s20, v254, 12
	v_lshl_or_b32 v148, s34, 7, v144
	v_readlane_b32 s21, v254, 13
	v_add_f32_e32 v147, 1.0, v147
	v_rcp_f32_e32 v152, v147
	v_mul_f32_e32 v147, 0xbfb8aa3b, v118
	v_exp_f32_e32 v147, v147
	v_lshl_add_u32 v146, s35, 8, v142
	v_ashrrev_i32_e32 v149, 31, v148
	v_mov_b64_e32 v[140:141], s[20:21]
	v_add_f32_e32 v147, 1.0, v147
	v_rcp_f32_e32 v154, v147
	v_mul_f32_e32 v147, 0xbfb8aa3b, v127
	v_exp_f32_e32 v147, v147
	s_movk_i32 s13, 0x1600
	v_mad_i64_i32 v[150:151], s[20:21], v146, s13, v[140:141]
	v_add_f32_e32 v147, 1.0, v147
	v_rcp_f32_e32 v153, v147
	s_andn2_b64 vcc, exec, s[6:7]
	v_pk_mul_f32 v[126:127], v[126:127], v[152:153]
	s_nop 0
	v_pk_mul_f32 v[122:123], v[126:127], v[122:123]
	v_mul_f32_e32 v126, 0xbfb8aa3b, v119
	v_exp_f32_e32 v126, v126
	s_nop 0
	v_add_f32_e32 v126, 1.0, v126
	v_rcp_f32_e32 v155, v126
	s_nop 0
	v_pk_mul_f32 v[118:119], v[118:119], v[154:155]
	s_nop 0
	v_pk_mul_f32 v[118:119], v[118:119], v[114:115]
	v_mul_f32_e32 v115, 0xbfb8aa3b, v120
	v_exp_f32_e32 v115, v115
	v_mul_f32_e32 v114, 0xbfb8aa3b, v128
	v_exp_f32_e32 v114, v114
	v_cvt_pk_bf16_f32 v118, v118, v119
	v_add_f32_e32 v115, 1.0, v115
	v_rcp_f32_e32 v126, v115
	v_mul_f32_e32 v115, 0xbfb8aa3b, v129
	v_exp_f32_e32 v115, v115
	v_add_f32_e32 v114, 1.0, v114
	v_rcp_f32_e32 v114, v114
	v_add_f32_e32 v115, 1.0, v115
	v_rcp_f32_e32 v115, v115
	s_nop 0
	v_pk_mul_f32 v[114:115], v[128:129], v[114:115]
	s_nop 0
	v_pk_mul_f32 v[124:125], v[114:115], v[124:125]
	v_mul_f32_e32 v114, 0xbfb8aa3b, v121
	v_exp_f32_e32 v114, v114
	s_nop 0
	v_add_f32_e32 v114, 1.0, v114
	v_rcp_f32_e32 v127, v114
	s_nop 0
	v_pk_mul_f32 v[114:115], v[120:121], v[126:127]
	s_nop 0
	v_pk_mul_f32 v[120:121], v[114:115], v[116:117]
	v_lshlrev_b64 v[114:115], 1, v[148:149]
	v_lshl_add_u64 v[126:127], v[150:151], 0, v[114:115]
	v_cvt_pk_bf16_f32 v116, v122, v123
	v_cvt_pk_bf16_f32 v117, v124, v125
	v_cvt_pk_bf16_f32 v119, v120, v121
	global_store_dwordx4 v[126:127], v[116:119], off nt
	s_nop 1
	v_mul_f32_e32 v119, 0xbfb8aa3b, v102
	v_exp_f32_e32 v119, v119
	v_mul_f32_e32 v118, 0xbfb8aa3b, v110
	v_exp_f32_e32 v118, v118
	v_or_b32_e32 v116, 16, v146
	v_add_f32_e32 v119, 1.0, v119
	v_rcp_f32_e32 v120, v119
	v_mul_f32_e32 v119, 0xbfb8aa3b, v111
	v_exp_f32_e32 v119, v119
	v_add_f32_e32 v118, 1.0, v118
	v_rcp_f32_e32 v118, v118
	v_mad_i64_i32 v[116:117], s[20:21], v116, s13, v[140:141]
	v_add_f32_e32 v119, 1.0, v119
	v_rcp_f32_e32 v119, v119
	s_nop 0
	v_pk_mul_f32 v[110:111], v[110:111], v[118:119]
	s_nop 0
	v_pk_mul_f32 v[106:107], v[110:111], v[106:107]
	v_mul_f32_e32 v110, 0xbfb8aa3b, v103
	v_exp_f32_e32 v110, v110
	s_nop 0
	v_add_f32_e32 v110, 1.0, v110
	v_rcp_f32_e32 v121, v110
	s_nop 0
	v_pk_mul_f32 v[102:103], v[102:103], v[120:121]
	s_nop 0
	v_pk_mul_f32 v[102:103], v[102:103], v[98:99]
	v_mul_f32_e32 v99, 0xbfb8aa3b, v104
	v_exp_f32_e32 v99, v99
	v_mul_f32_e32 v98, 0xbfb8aa3b, v112
	v_exp_f32_e32 v98, v98
	v_add_f32_e32 v99, 1.0, v99
	v_rcp_f32_e32 v110, v99
	v_mul_f32_e32 v99, 0xbfb8aa3b, v113
	v_exp_f32_e32 v99, v99
	v_add_f32_e32 v98, 1.0, v98
	v_rcp_f32_e32 v98, v98
	v_add_f32_e32 v99, 1.0, v99
	v_rcp_f32_e32 v99, v99
	s_nop 0
	v_pk_mul_f32 v[98:99], v[112:113], v[98:99]
	s_nop 0
	v_pk_mul_f32 v[108:109], v[98:99], v[108:109]
	v_mul_f32_e32 v98, 0xbfb8aa3b, v105
	v_exp_f32_e32 v98, v98
	s_nop 0
	v_add_f32_e32 v98, 1.0, v98
	v_rcp_f32_e32 v111, v98
	s_nop 0
	v_pk_mul_f32 v[98:99], v[104:105], v[110:111]
	s_nop 0
	v_pk_mul_f32 v[104:105], v[98:99], v[100:101]
	v_lshl_add_u64 v[110:111], v[116:117], 0, v[114:115]
	v_cvt_pk_bf16_f32 v98, v106, v107
	v_cvt_pk_bf16_f32 v99, v108, v109
	v_cvt_pk_bf16_f32 v100, v102, v103
	v_cvt_pk_bf16_f32 v101, v104, v105
	global_store_dwordx4 v[110:111], v[98:101], off nt
	s_nop 1
	v_mul_f32_e32 v101, 0xbfb8aa3b, v86
	v_exp_f32_e32 v101, v101
	v_mul_f32_e32 v100, 0xbfb8aa3b, v94
	v_exp_f32_e32 v100, v100
	v_or_b32_e32 v98, 32, v146
	v_add_f32_e32 v101, 1.0, v101
	v_rcp_f32_e32 v102, v101
	v_mul_f32_e32 v101, 0xbfb8aa3b, v95
	v_exp_f32_e32 v101, v101
	v_add_f32_e32 v100, 1.0, v100
	v_rcp_f32_e32 v100, v100
	v_mad_i64_i32 v[98:99], s[20:21], v98, s13, v[140:141]
	v_add_f32_e32 v101, 1.0, v101
	v_rcp_f32_e32 v101, v101
	s_nop 0
	v_pk_mul_f32 v[94:95], v[94:95], v[100:101]
	s_nop 0
	v_pk_mul_f32 v[90:91], v[94:95], v[90:91]
	v_mul_f32_e32 v94, 0xbfb8aa3b, v87
	v_exp_f32_e32 v94, v94
	s_nop 0
	v_add_f32_e32 v94, 1.0, v94
	v_rcp_f32_e32 v103, v94
	s_nop 0
	v_pk_mul_f32 v[86:87], v[86:87], v[102:103]
	s_nop 0
	v_pk_mul_f32 v[86:87], v[86:87], v[82:83]
	v_mul_f32_e32 v83, 0xbfb8aa3b, v88
	v_exp_f32_e32 v83, v83
	v_mul_f32_e32 v82, 0xbfb8aa3b, v96
	v_exp_f32_e32 v82, v82
	v_add_f32_e32 v83, 1.0, v83
	v_rcp_f32_e32 v94, v83
	v_mul_f32_e32 v83, 0xbfb8aa3b, v97
	v_exp_f32_e32 v83, v83
	v_add_f32_e32 v82, 1.0, v82
	v_rcp_f32_e32 v82, v82
	v_add_f32_e32 v83, 1.0, v83
	v_rcp_f32_e32 v83, v83
	s_nop 0
	v_pk_mul_f32 v[82:83], v[96:97], v[82:83]
	s_nop 0
	v_pk_mul_f32 v[92:93], v[82:83], v[92:93]
	v_mul_f32_e32 v82, 0xbfb8aa3b, v89
	v_exp_f32_e32 v82, v82
	s_nop 0
	v_add_f32_e32 v82, 1.0, v82
	v_rcp_f32_e32 v95, v82
	s_nop 0
	v_pk_mul_f32 v[82:83], v[88:89], v[94:95]
	s_nop 0
	v_pk_mul_f32 v[88:89], v[82:83], v[84:85]
	v_lshl_add_u64 v[94:95], v[98:99], 0, v[114:115]
	v_cvt_pk_bf16_f32 v82, v90, v91
	v_cvt_pk_bf16_f32 v83, v92, v93
	v_cvt_pk_bf16_f32 v84, v86, v87
	v_cvt_pk_bf16_f32 v85, v88, v89
	global_store_dwordx4 v[94:95], v[82:85], off nt
	s_nop 1
	v_mul_f32_e32 v85, 0xbfb8aa3b, v70
	v_exp_f32_e32 v85, v85
	v_mul_f32_e32 v84, 0xbfb8aa3b, v78
	v_exp_f32_e32 v84, v84
	v_or_b32_e32 v82, 48, v146
	v_add_f32_e32 v85, 1.0, v85
	v_rcp_f32_e32 v86, v85
	v_mul_f32_e32 v85, 0xbfb8aa3b, v79
	v_exp_f32_e32 v85, v85
	v_add_f32_e32 v84, 1.0, v84
	v_rcp_f32_e32 v84, v84
	v_mad_i64_i32 v[82:83], s[20:21], v82, s13, v[140:141]
	v_add_f32_e32 v85, 1.0, v85
	v_rcp_f32_e32 v85, v85
	s_nop 0
	v_pk_mul_f32 v[78:79], v[78:79], v[84:85]
	s_nop 0
	v_pk_mul_f32 v[74:75], v[78:79], v[74:75]
	v_mul_f32_e32 v78, 0xbfb8aa3b, v71
	v_exp_f32_e32 v78, v78
	s_nop 0
	v_add_f32_e32 v78, 1.0, v78
	v_rcp_f32_e32 v87, v78
	s_nop 0
	v_pk_mul_f32 v[70:71], v[70:71], v[86:87]
	s_nop 0
	v_pk_mul_f32 v[70:71], v[70:71], v[66:67]
	v_mul_f32_e32 v67, 0xbfb8aa3b, v72
	v_exp_f32_e32 v67, v67
	v_mul_f32_e32 v66, 0xbfb8aa3b, v80
	v_exp_f32_e32 v66, v66
	v_add_f32_e32 v67, 1.0, v67
	v_rcp_f32_e32 v78, v67
	v_mul_f32_e32 v67, 0xbfb8aa3b, v81
	v_exp_f32_e32 v67, v67
	v_add_f32_e32 v66, 1.0, v66
	v_rcp_f32_e32 v66, v66
	v_add_f32_e32 v67, 1.0, v67
	v_rcp_f32_e32 v67, v67
	s_nop 0
	v_pk_mul_f32 v[66:67], v[80:81], v[66:67]
	s_nop 0
	v_pk_mul_f32 v[76:77], v[66:67], v[76:77]
	v_mul_f32_e32 v66, 0xbfb8aa3b, v73
	v_exp_f32_e32 v66, v66
	s_nop 0
	v_add_f32_e32 v66, 1.0, v66
	v_rcp_f32_e32 v79, v66
	s_nop 0
	v_pk_mul_f32 v[66:67], v[72:73], v[78:79]
	s_nop 0
	v_pk_mul_f32 v[72:73], v[66:67], v[68:69]
	v_lshl_add_u64 v[78:79], v[82:83], 0, v[114:115]
	v_cvt_pk_bf16_f32 v66, v74, v75
	v_cvt_pk_bf16_f32 v67, v76, v77
	v_cvt_pk_bf16_f32 v68, v70, v71
	v_cvt_pk_bf16_f32 v69, v72, v73
	global_store_dwordx4 v[78:79], v[66:69], off nt
	s_nop 1
	v_mul_f32_e32 v69, 0xbfb8aa3b, v54
	v_exp_f32_e32 v69, v69
	v_mul_f32_e32 v68, 0xbfb8aa3b, v62
	v_exp_f32_e32 v68, v68
	v_add_u32_e32 v66, 0x80, v146
	v_add_f32_e32 v69, 1.0, v69
	v_rcp_f32_e32 v70, v69
	v_mul_f32_e32 v69, 0xbfb8aa3b, v63
	v_exp_f32_e32 v69, v69
	v_add_f32_e32 v68, 1.0, v68
	v_rcp_f32_e32 v68, v68
	v_mad_i64_i32 v[66:67], s[20:21], v66, s13, v[140:141]
	v_add_f32_e32 v69, 1.0, v69
	v_rcp_f32_e32 v69, v69
	s_nop 0
	v_pk_mul_f32 v[62:63], v[62:63], v[68:69]
	s_nop 0
	v_pk_mul_f32 v[58:59], v[62:63], v[58:59]
	v_mul_f32_e32 v62, 0xbfb8aa3b, v55
	v_exp_f32_e32 v62, v62
	s_nop 0
	v_add_f32_e32 v62, 1.0, v62
	v_rcp_f32_e32 v71, v62
	s_nop 0
	v_pk_mul_f32 v[54:55], v[54:55], v[70:71]
	s_nop 0
	v_pk_mul_f32 v[54:55], v[54:55], v[50:51]
	v_mul_f32_e32 v51, 0xbfb8aa3b, v56
	v_exp_f32_e32 v51, v51
	v_mul_f32_e32 v50, 0xbfb8aa3b, v64
	v_exp_f32_e32 v50, v50
	v_add_f32_e32 v51, 1.0, v51
	v_rcp_f32_e32 v62, v51
	v_mul_f32_e32 v51, 0xbfb8aa3b, v65
	v_exp_f32_e32 v51, v51
	v_add_f32_e32 v50, 1.0, v50
	v_rcp_f32_e32 v50, v50
	v_add_f32_e32 v51, 1.0, v51
	v_rcp_f32_e32 v51, v51
	s_nop 0
	v_pk_mul_f32 v[50:51], v[64:65], v[50:51]
	s_nop 0
	v_pk_mul_f32 v[60:61], v[50:51], v[60:61]
	v_mul_f32_e32 v50, 0xbfb8aa3b, v57
	v_exp_f32_e32 v50, v50
	s_nop 0
	v_add_f32_e32 v50, 1.0, v50
	v_rcp_f32_e32 v63, v50
	s_nop 0
	v_pk_mul_f32 v[50:51], v[56:57], v[62:63]
	s_nop 0
	v_pk_mul_f32 v[56:57], v[50:51], v[52:53]
	v_lshl_add_u64 v[62:63], v[66:67], 0, v[114:115]
	v_cvt_pk_bf16_f32 v50, v58, v59
	v_cvt_pk_bf16_f32 v51, v60, v61
	v_cvt_pk_bf16_f32 v52, v54, v55
	v_cvt_pk_bf16_f32 v53, v56, v57
	global_store_dwordx4 v[62:63], v[50:53], off nt
	s_nop 1
	v_mul_f32_e32 v53, 0xbfb8aa3b, v38
	v_exp_f32_e32 v53, v53
	v_mul_f32_e32 v52, 0xbfb8aa3b, v46
	v_exp_f32_e32 v52, v52
	v_add_u32_e32 v50, 0x90, v146
	v_add_f32_e32 v53, 1.0, v53
	v_rcp_f32_e32 v54, v53
	v_mul_f32_e32 v53, 0xbfb8aa3b, v47
	v_exp_f32_e32 v53, v53
	v_add_f32_e32 v52, 1.0, v52
	v_rcp_f32_e32 v52, v52
	v_mad_i64_i32 v[50:51], s[20:21], v50, s13, v[140:141]
	v_add_f32_e32 v53, 1.0, v53
	v_rcp_f32_e32 v53, v53
	s_nop 0
	v_pk_mul_f32 v[46:47], v[46:47], v[52:53]
	s_nop 0
	v_pk_mul_f32 v[42:43], v[46:47], v[42:43]
	v_mul_f32_e32 v46, 0xbfb8aa3b, v39
	v_exp_f32_e32 v46, v46
	s_nop 0
	v_add_f32_e32 v46, 1.0, v46
	v_rcp_f32_e32 v55, v46
	s_nop 0
	v_pk_mul_f32 v[38:39], v[38:39], v[54:55]
	s_nop 0
	v_pk_mul_f32 v[38:39], v[38:39], v[34:35]
	v_mul_f32_e32 v35, 0xbfb8aa3b, v40
	v_exp_f32_e32 v35, v35
	v_mul_f32_e32 v34, 0xbfb8aa3b, v48
	v_exp_f32_e32 v34, v34
	v_add_f32_e32 v35, 1.0, v35
	v_rcp_f32_e32 v46, v35
	v_mul_f32_e32 v35, 0xbfb8aa3b, v49
	v_exp_f32_e32 v35, v35
	v_add_f32_e32 v34, 1.0, v34
	v_rcp_f32_e32 v34, v34
	v_add_f32_e32 v35, 1.0, v35
	v_rcp_f32_e32 v35, v35
	s_nop 0
	v_pk_mul_f32 v[34:35], v[48:49], v[34:35]
	s_nop 0
	v_pk_mul_f32 v[44:45], v[34:35], v[44:45]
	v_mul_f32_e32 v34, 0xbfb8aa3b, v41
	v_exp_f32_e32 v34, v34
	s_nop 0
	v_add_f32_e32 v34, 1.0, v34
	v_rcp_f32_e32 v47, v34
	s_nop 0
	v_pk_mul_f32 v[34:35], v[40:41], v[46:47]
	s_nop 0
	v_pk_mul_f32 v[40:41], v[34:35], v[36:37]
	v_lshl_add_u64 v[46:47], v[50:51], 0, v[114:115]
	v_cvt_pk_bf16_f32 v34, v42, v43
	v_cvt_pk_bf16_f32 v35, v44, v45
	v_cvt_pk_bf16_f32 v36, v38, v39
	v_cvt_pk_bf16_f32 v37, v40, v41
	global_store_dwordx4 v[46:47], v[34:37], off nt
	s_nop 1
	v_mul_f32_e32 v37, 0xbfb8aa3b, v22
	v_exp_f32_e32 v37, v37
	v_mul_f32_e32 v36, 0xbfb8aa3b, v30
	v_exp_f32_e32 v36, v36
	v_add_u32_e32 v34, 0xa0, v146
	v_add_f32_e32 v37, 1.0, v37
	v_rcp_f32_e32 v38, v37
	v_mul_f32_e32 v37, 0xbfb8aa3b, v31
	v_exp_f32_e32 v37, v37
	v_add_f32_e32 v36, 1.0, v36
	v_rcp_f32_e32 v36, v36
	v_mad_i64_i32 v[34:35], s[20:21], v34, s13, v[140:141]
	v_add_f32_e32 v37, 1.0, v37
	v_rcp_f32_e32 v37, v37
	s_nop 0
	v_pk_mul_f32 v[30:31], v[30:31], v[36:37]
	s_nop 0
	v_pk_mul_f32 v[26:27], v[30:31], v[26:27]
	v_mul_f32_e32 v30, 0xbfb8aa3b, v23
	v_exp_f32_e32 v30, v30
	s_nop 0
	v_add_f32_e32 v30, 1.0, v30
	v_rcp_f32_e32 v39, v30
	s_nop 0
	v_pk_mul_f32 v[22:23], v[22:23], v[38:39]
	s_nop 0
	v_pk_mul_f32 v[22:23], v[22:23], v[18:19]
	v_mul_f32_e32 v19, 0xbfb8aa3b, v24
	v_exp_f32_e32 v19, v19
	v_mul_f32_e32 v18, 0xbfb8aa3b, v32
	v_exp_f32_e32 v18, v18
	v_add_f32_e32 v19, 1.0, v19
	v_rcp_f32_e32 v30, v19
	v_mul_f32_e32 v19, 0xbfb8aa3b, v33
	v_exp_f32_e32 v19, v19
	v_add_f32_e32 v18, 1.0, v18
	v_rcp_f32_e32 v18, v18
	v_add_f32_e32 v19, 1.0, v19
	v_rcp_f32_e32 v19, v19
	s_nop 0
	v_pk_mul_f32 v[18:19], v[32:33], v[18:19]
	s_nop 0
	v_pk_mul_f32 v[28:29], v[18:19], v[28:29]
	v_mul_f32_e32 v18, 0xbfb8aa3b, v25
	v_exp_f32_e32 v18, v18
	s_nop 0
	v_add_f32_e32 v18, 1.0, v18
	v_rcp_f32_e32 v31, v18
	s_nop 0
	v_pk_mul_f32 v[18:19], v[24:25], v[30:31]
	s_nop 0
	v_pk_mul_f32 v[24:25], v[18:19], v[20:21]
	v_lshl_add_u64 v[30:31], v[34:35], 0, v[114:115]
	v_cvt_pk_bf16_f32 v18, v26, v27
	v_cvt_pk_bf16_f32 v19, v28, v29
	v_cvt_pk_bf16_f32 v20, v22, v23
	v_cvt_pk_bf16_f32 v21, v24, v25
	global_store_dwordx4 v[30:31], v[18:21], off nt
	s_nop 1
	v_mul_f32_e32 v21, 0xbfb8aa3b, v6
	v_exp_f32_e32 v21, v21
	v_mul_f32_e32 v20, 0xbfb8aa3b, v14
	v_exp_f32_e32 v20, v20
	v_add_u32_e32 v18, 0xb0, v146
	v_add_f32_e32 v21, 1.0, v21
	v_rcp_f32_e32 v22, v21
	v_mul_f32_e32 v21, 0xbfb8aa3b, v15
	v_exp_f32_e32 v21, v21
	v_add_f32_e32 v20, 1.0, v20
	v_rcp_f32_e32 v20, v20
	v_mad_i64_i32 v[18:19], s[20:21], v18, s13, v[140:141]
	v_add_f32_e32 v21, 1.0, v21
	v_rcp_f32_e32 v21, v21
	s_mov_b64 s[20:21], -1
	v_pk_mul_f32 v[14:15], v[14:15], v[20:21]
	s_nop 0
	v_pk_mul_f32 v[10:11], v[14:15], v[10:11]
	v_mul_f32_e32 v14, 0xbfb8aa3b, v7
	v_exp_f32_e32 v14, v14
	s_nop 0
	v_add_f32_e32 v14, 1.0, v14
	v_rcp_f32_e32 v23, v14
	s_nop 0
	v_pk_mul_f32 v[6:7], v[6:7], v[22:23]
	s_nop 0
	v_pk_mul_f32 v[6:7], v[6:7], v[2:3]
	v_mul_f32_e32 v3, 0xbfb8aa3b, v8
	v_exp_f32_e32 v3, v3
	v_mul_f32_e32 v2, 0xbfb8aa3b, v16
	v_exp_f32_e32 v2, v2
	v_add_f32_e32 v3, 1.0, v3
	v_rcp_f32_e32 v14, v3
	v_mul_f32_e32 v3, 0xbfb8aa3b, v17
	v_exp_f32_e32 v3, v3
	v_add_f32_e32 v2, 1.0, v2
	v_rcp_f32_e32 v2, v2
	v_add_f32_e32 v3, 1.0, v3
	v_rcp_f32_e32 v3, v3
	s_nop 0
	v_pk_mul_f32 v[2:3], v[16:17], v[2:3]
	s_nop 0
	v_pk_mul_f32 v[12:13], v[2:3], v[12:13]
	v_mul_f32_e32 v2, 0xbfb8aa3b, v9
	v_exp_f32_e32 v2, v2
	s_nop 0
	v_add_f32_e32 v2, 1.0, v2
	v_rcp_f32_e32 v15, v2
	s_nop 0
	v_pk_mul_f32 v[2:3], v[8:9], v[14:15]
	s_nop 0
	v_pk_mul_f32 v[8:9], v[2:3], v[4:5]
	v_lshl_add_u64 v[14:15], v[18:19], 0, v[114:115]
	v_cvt_pk_bf16_f32 v2, v10, v11
	v_cvt_pk_bf16_f32 v3, v12, v13
	v_cvt_pk_bf16_f32 v4, v6, v7
	v_cvt_pk_bf16_f32 v5, v8, v9
	global_store_dwordx4 v[14:15], v[2:5], off nt
	s_cbranch_vccnz .LBB0_680
	s_andn2_b64 vcc, exec, s[8:9]
	s_cbranch_vccnz .LBB0_679
	s_barrier
	s_branch .LBB0_679
